# GEMM main loops: static priority raise for waves 0-3 instead of 4-7 (toggles removed)
# speedup vs baseline: 1.0026x; 1.0026x over previous
.LBB0_410:
	s_cmp_lt_i32 s68, 3
	s_cselect_b64 s[4:5], -1, 0
	s_and_b64 s[4:5], s[4:5], s[0:1]
	s_andn2_b64 vcc, exec, s[4:5]
	s_cbranch_vccnz .LBB0_431
	v_readfirstlane_b32 s101, v145
	s_cmp_lt_u32 s101, 4
	s_cbranch_scc0 .Lprio_2
	s_setprio 1

.LBB0_673:
	s_cmp_lt_i32 s68, 5
	s_cselect_b64 s[4:5], -1, 0
	s_and_b64 s[4:5], s[4:5], s[0:1]
	s_andn2_b64 vcc, exec, s[4:5]
	s_cbranch_vccnz .LBB0_694
	v_readfirstlane_b32 s101, v145
	s_cmp_lt_u32 s101, 4
	s_cbranch_scc0 .Lprio_4
	s_setprio 1

.LBB0_801:
	s_cmp_lt_i32 s68, 7
	s_cselect_b64 s[4:5], -1, 0
	s_and_b64 s[4:5], s[4:5], s[0:1]
	s_andn2_b64 vcc, exec, s[4:5]
	s_cbranch_vccnz .LBB0_818
	v_readfirstlane_b32 s101, v145
	s_cmp_lt_u32 s101, 4
	s_cbranch_scc0 .Lprio_6
	s_setprio 1

.LBB0_868:
	s_cmp_lt_i32 s68, 8
	s_cselect_b64 s[4:5], -1, 0
	s_and_b64 s[6:7], s[4:5], s[0:1]
	s_andn2_b64 vcc, exec, s[6:7]
	s_cbranch_vccnz .LBB0_893
	v_readfirstlane_b32 s101, v145
	s_cmp_lt_u32 s101, 4
	s_cbranch_scc0 .Lprio_7
	s_setprio 1

.LBB0_1000:
	s_cmp_lt_i32 s68, 10
	s_cselect_b64 s[4:5], -1, 0
	s_and_b64 s[4:5], s[4:5], s[0:1]
	s_andn2_b64 vcc, exec, s[4:5]
	s_cbranch_vccnz .LBB0_1035
	v_readfirstlane_b32 s101, v145
	s_cmp_lt_u32 s101, 4
	s_cbranch_scc0 .Lprio_9
	s_setprio 1

.LBB0_2408:
	s_cmp_lt_i32 s68, 13
	s_cselect_b64 s[4:5], -1, 0
	s_and_b64 s[4:5], s[4:5], s[0:1]
	s_andn2_b64 vcc, exec, s[4:5]
	s_cbranch_vccnz .LBB0_2429
	v_readfirstlane_b32 s101, v145
	s_cmp_lt_u32 s101, 4
	s_cbranch_scc0 .Lprio_12
	s_setprio 1

.LBB0_2536:
	s_cmp_lt_i32 s68, 15
	s_cselect_b64 s[4:5], -1, 0
	s_and_b64 s[4:5], s[4:5], s[0:1]
	s_andn2_b64 vcc, exec, s[4:5]
	s_cbranch_vccnz .LBB0_2553
	v_readfirstlane_b32 s101, v145
	s_cmp_lt_u32 s101, 4
	s_cbranch_scc0 .Lprio_14
	s_setprio 1

.LBB0_2603:
	s_cmp_lt_i32 s68, 16
	s_cselect_b64 s[4:5], -1, 0
	s_and_b64 s[6:7], s[4:5], s[0:1]
	s_andn2_b64 vcc, exec, s[6:7]
	s_cbranch_vccnz .LBB0_2628
	v_readfirstlane_b32 s101, v145
	s_cmp_lt_u32 s101, 4
	s_cbranch_scc0 .Lprio_15
	s_setprio 1
